# speedup vs baseline: 1.0217x; 1.0062x over previous
; DI unsigned cvtpk(float lo, float hi) { f32x2_t v = {lo, hi}; bf16x2_t b = __builtin_convertvector(v, bf16x2_t); return __builtin_bit_cast(unsigned, b); }
; DI void ln_row2(float* y0, float* y1, bf16_t* xb0, bf16_t* xb1, const float* g, const float* b, int lane) {
;     f32x4* xr0 = (f32x4*)y0 + lane; f32x4* xr1 = (f32x4*)y1 + lane;
;     f32x4 v0[4], v1[4]; float s0 = 0.f, s1 = 0.f;
; #pragma unroll
;     for (int j = 0; j < 4; ++j) { v0[j] = xr0[64 * j]; v1[j] = xr1[64 * j]; }
; #pragma unroll
;     for (int j = 0; j < 4; ++j) { s0 += (v0[j].x + v0[j].y) + (v0[j].z + v0[j].w); s1 += (v1[j].x + v1[j].y) + (v1[j].z + v1[j].w); }
; #pragma unroll
;     for (int o = 1; o < 64; o <<= 1) { s0 += __shfl_xor(s0, o); s1 += __shfl_xor(s1, o); }
;     const float m0 = s0 * (1.f / DM), m1 = s1 * (1.f / DM); float q0 = 0.f, q1 = 0.f;
; #pragma unroll
;     for (int j = 0; j < 4; ++j) { v0[j] = v0[j] - m0; v1[j] = v1[j] - m1;
;         q0 += (v0[j].x * v0[j].x + v0[j].y * v0[j].y) + (v0[j].z * v0[j].z + v0[j].w * v0[j].w);
;         q1 += (v1[j].x * v1[j].x + v1[j].y * v1[j].y) + (v1[j].z * v1[j].z + v1[j].w * v1[j].w); }
; #pragma unroll
;     for (int o = 1; o < 64; o <<= 1) { q0 += __shfl_xor(q0, o); q1 += __shfl_xor(q1, o); }
;     const float r0 = 1.f / sqrtf(q0 * (1.f / DM) + EPS), r1 = 1.f / sqrtf(q1 * (1.f / DM) + EPS);
;     u32x2* o80 = (u32x2*)xb0 + lane; u32x2* o81 = (u32x2*)xb1 + lane;
; #pragma unroll
;     for (int j = 0; j < 4; ++j) {
;         const f32x4 gg = ((const f32x4*)g)[lane + 64 * j], bb = ((const f32x4*)b)[lane + 64 * j];
;         const f32x4 a = v0[j] * r0 * gg + bb, c = v1[j] * r1 * gg + bb;
;         xr0[64 * j] = a; xr1[64 * j] = c;
;         u32x2 w; w.x = cvtpk(a.x, a.y); w.y = cvtpk(a.z, a.w); o80[64 * j] = w;
;         u32x2 w2; w2.x = cvtpk(c.x, c.y); w2.y = cvtpk(c.z, c.w); o81[64 * j] = w2;
;     }
; DI void ln_phase(unsigned char* lds, int l, int which) {
;     ...
;         __syncthreads();
;         for (int m = MP + bid * 64 + wid; m < MP + bid * 64 + 64; m += 16) ln_row2(Y + (size_t)m * DM, Y + (size_t)(m + 8) * DM, XB + (size_t)m * DM, XB + (size_t)(m + 8) * DM, g, b, lane);
.LBB0_381:
	s_or_b64 exec, exec, s[40:41]
	s_lshl_b32 s4, s72, 6
	v_add_u32_e32 v2, s4, v162
	v_add_u32_e32 v34, 0x8000, v2
	s_add_i32 s4, s4, 0x8040
	v_cmp_gt_i32_e32 vcc, s4, v34
	s_barrier
	s_and_saveexec_b64 s[42:43], vcc
	s_mov_b32 s5, 0xf800000
	s_mov_b32 s8, 0x3a00000
	s_mov_b64 s[48:49], 0x8000
	s_mov_b64 s[50:51], 0x10000
	s_cbranch_execz .LBB0_384
	s_mov_b64 s[42:43], exec
	s_add_u32 s50, s46, 0x3a00000
	s_addc_u32 s51, s47, 0
	v_readfirstlane_b32 s4, v162
	s_lshl_b32 s6, s72, 6
	s_add_i32 s4, s4, s6
	s_add_i32 s4, s4, 0x8000
	s_add_i32 s52, s6, 0x8040
	s_mov_b32 s5, 8
	v_lshlrev_b32_e32 v2, 4, v1
	v_lshlrev_b32_e32 v3, 3, v1
	global_load_dwordx4 v[4:7], v2, s[58:59]
	global_load_dwordx4 v[8:11], v2, s[58:59] offset:1024
	global_load_dwordx4 v[12:15], v2, s[58:59] offset:2048
	global_load_dwordx4 v[16:19], v2, s[58:59] offset:3072
	global_load_dwordx4 v[20:23], v2, s[60:61]
	global_load_dwordx4 v[24:27], v2, s[60:61] offset:1024
	global_load_dwordx4 v[28:31], v2, s[60:61] offset:2048
	global_load_dwordx4 v[32:35], v2, s[60:61] offset:3072
	s_lshl_b32 s34, s5, 12
	s_lshl_b32 s35, s5, 11
	s_lshl_b32 s6, s4, 12
	s_add_u32 s8, s44, s6
	s_addc_u32 s9, s45, 0
	s_lshl_b32 s6, s4, 11
	s_add_u32 s10, s50, s6
	s_addc_u32 s11, s51, 0
	s_mov_b32 s6, s8
	s_mov_b32 s7, s9
	s_mov_b32 s54, s4
	global_load_dwordx4 v[36:39], v2, s[6:7] nt
	global_load_dwordx4 v[40:43], v2, s[6:7] offset:1024 nt
	global_load_dwordx4 v[44:47], v2, s[6:7] offset:2048 nt
	global_load_dwordx4 v[48:51], v2, s[6:7] offset:3072 nt
	s_add_u32 s6, s6, s34
	s_addc_u32 s7, s7, 0
	s_add_i32 s54, s54, s5
	global_load_dwordx4 v[52:55], v2, s[6:7] nt
	global_load_dwordx4 v[56:59], v2, s[6:7] offset:1024 nt
	global_load_dwordx4 v[60:63], v2, s[6:7] offset:2048 nt
	global_load_dwordx4 v[64:67], v2, s[6:7] offset:3072 nt
	s_add_u32 s6, s6, s34
	s_addc_u32 s7, s7, 0
	s_add_i32 s54, s54, s5
	s_waitcnt vmcnt(4)
.Lmy_lns0_b0:
	s_cmp_ge_i32 s54, s52
	s_cbranch_scc1 .Lmy_lns0_n0
	global_load_dwordx4 v[68:71], v2, s[6:7] nt
	global_load_dwordx4 v[72:75], v2, s[6:7] offset:1024 nt
	global_load_dwordx4 v[76:79], v2, s[6:7] offset:2048 nt
	global_load_dwordx4 v[80:83], v2, s[6:7] offset:3072 nt
	s_add_u32 s6, s6, s34
	s_addc_u32 s7, s7, 0
	s_add_i32 s54, s54, s5
.Lmy_lns0_n0:
	s_waitcnt vmcnt(16)
	v_add_f32_e32 v84, v36, v37
	v_add_f32_e32 v85, v38, v39
	v_add_f32_e32 v86, v40, v41
	v_add_f32_e32 v87, v42, v43
	v_add_f32_e32 v88, v44, v45
	v_add_f32_e32 v89, v46, v47
	v_add_f32_e32 v90, v48, v49
	v_add_f32_e32 v91, v50, v51
	v_add_f32_e32 v84, v84, v85
	v_add_f32_e32 v86, v86, v87
	v_add_f32_e32 v88, v88, v89
	v_add_f32_e32 v90, v90, v91
	v_add_f32_e32 v84, v84, v86
	v_add_f32_e32 v88, v88, v90
	v_add_f32_e32 v84, v84, v88
	s_nop 1
	v_add_f32_dpp v84, v84, v84 quad_perm:[1,0,3,2] row_mask:0xf bank_mask:0xf
	s_nop 1
	v_add_f32_dpp v84, v84, v84 quad_perm:[2,3,0,1] row_mask:0xf bank_mask:0xf
	s_nop 1
	v_add_f32_dpp v84, v84, v84 row_half_mirror row_mask:0xf bank_mask:0xf
	s_nop 1
	v_add_f32_dpp v84, v84, v84 row_mirror row_mask:0xf bank_mask:0xf
	s_nop 1
	v_add_f32_dpp v84, v84, v84 row_bcast:15 row_mask:0xa bank_mask:0xf
	s_nop 1
	v_add_f32_dpp v84, v84, v84 row_bcast:31 row_mask:0xc bank_mask:0xf
	s_nop 1
	v_readlane_b32 s55, v84, 63
	s_nop 1
	v_mov_b32_e32 v85, s55
	v_mul_f32_e32 v85, 0x3a800000, v85
	v_sub_f32_e32 v36, v36, v85
	v_sub_f32_e32 v37, v37, v85
	v_sub_f32_e32 v38, v38, v85
	v_sub_f32_e32 v39, v39, v85
	v_sub_f32_e32 v40, v40, v85
	v_sub_f32_e32 v41, v41, v85
	v_sub_f32_e32 v42, v42, v85
	v_sub_f32_e32 v43, v43, v85
	v_sub_f32_e32 v44, v44, v85
	v_sub_f32_e32 v45, v45, v85
	v_sub_f32_e32 v46, v46, v85
	v_sub_f32_e32 v47, v47, v85
	v_sub_f32_e32 v48, v48, v85
	v_sub_f32_e32 v49, v49, v85
	v_sub_f32_e32 v50, v50, v85
	v_sub_f32_e32 v51, v51, v85
	v_mul_f32_e32 v88, v36, v36
	v_mul_f32_e32 v89, v37, v37
	v_mul_f32_e32 v90, v38, v38
	v_mul_f32_e32 v91, v39, v39
	v_fmac_f32_e32 v88, v40, v40
	v_fmac_f32_e32 v89, v41, v41
	v_fmac_f32_e32 v90, v42, v42
	v_fmac_f32_e32 v91, v43, v43
	v_fmac_f32_e32 v88, v44, v44
	v_fmac_f32_e32 v89, v45, v45
	v_fmac_f32_e32 v90, v46, v46
	v_fmac_f32_e32 v91, v47, v47
	v_fmac_f32_e32 v88, v48, v48
	v_fmac_f32_e32 v89, v49, v49
	v_fmac_f32_e32 v90, v50, v50
	v_fmac_f32_e32 v91, v51, v51
	v_add_f32_e32 v88, v88, v89
	v_add_f32_e32 v90, v90, v91
	v_add_f32_e32 v88, v88, v90
	s_nop 1
	v_add_f32_dpp v88, v88, v88 quad_perm:[1,0,3,2] row_mask:0xf bank_mask:0xf
	s_nop 1
	v_add_f32_dpp v88, v88, v88 quad_perm:[2,3,0,1] row_mask:0xf bank_mask:0xf
	s_nop 1
	v_add_f32_dpp v88, v88, v88 row_half_mirror row_mask:0xf bank_mask:0xf
	s_nop 1
	v_add_f32_dpp v88, v88, v88 row_mirror row_mask:0xf bank_mask:0xf
	s_nop 1
	v_add_f32_dpp v88, v88, v88 row_bcast:15 row_mask:0xa bank_mask:0xf
	s_nop 1
	v_add_f32_dpp v88, v88, v88 row_bcast:31 row_mask:0xc bank_mask:0xf
	s_nop 1
	v_readlane_b32 s55, v88, 63
	s_nop 1
	v_mov_b32_e32 v89, s55
	v_fmamk_f32 v89, v89, 0x3a800000, v214
	v_rsq_f32_e32 v90, v89
	s_nop 0
	v_mul_f32_e32 v91, v89, v90
	v_mul_f32_e32 v91, v91, v90
	v_mul_f32_e32 v91, -0.5, v91
	v_add_f32_e32 v91, 0x3fc00000, v91
	v_mul_f32_e32 v90, v90, v91
	v_pk_mul_f32 v[36:37], v[36:37], v[90:91] op_sel_hi:[1,0]
	v_pk_mul_f32 v[38:39], v[38:39], v[90:91] op_sel_hi:[1,0]
	v_pk_mul_f32 v[40:41], v[40:41], v[90:91] op_sel_hi:[1,0]
	v_pk_mul_f32 v[42:43], v[42:43], v[90:91] op_sel_hi:[1,0]
	v_pk_mul_f32 v[44:45], v[44:45], v[90:91] op_sel_hi:[1,0]
	v_pk_mul_f32 v[46:47], v[46:47], v[90:91] op_sel_hi:[1,0]
	v_pk_mul_f32 v[48:49], v[48:49], v[90:91] op_sel_hi:[1,0]
	v_pk_mul_f32 v[50:51], v[50:51], v[90:91] op_sel_hi:[1,0]
	v_pk_fma_f32 v[36:37], v[36:37], v[4:5], v[20:21]
	v_pk_fma_f32 v[38:39], v[38:39], v[6:7], v[22:23]
	v_pk_fma_f32 v[40:41], v[40:41], v[8:9], v[24:25]
	v_pk_fma_f32 v[42:43], v[42:43], v[10:11], v[26:27]
	v_pk_fma_f32 v[44:45], v[44:45], v[12:13], v[28:29]
	v_pk_fma_f32 v[46:47], v[46:47], v[14:15], v[30:31]
	v_pk_fma_f32 v[48:49], v[48:49], v[16:17], v[32:33]
	v_pk_fma_f32 v[50:51], v[50:51], v[18:19], v[34:35]
	v_cvt_pk_bf16_f32 v100, v36, v37
	v_cvt_pk_bf16_f32 v101, v38, v39
	v_cvt_pk_bf16_f32 v102, v40, v41
	v_cvt_pk_bf16_f32 v103, v42, v43
	v_cvt_pk_bf16_f32 v104, v44, v45
	v_cvt_pk_bf16_f32 v105, v46, v47
	v_cvt_pk_bf16_f32 v106, v48, v49
	v_cvt_pk_bf16_f32 v107, v50, v51
	global_store_dwordx4 v2, v[36:39], s[8:9] nt
	global_store_dwordx4 v2, v[40:43], s[8:9] offset:1024 nt
	global_store_dwordx4 v2, v[44:47], s[8:9] offset:2048 nt
	global_store_dwordx4 v2, v[48:51], s[8:9] offset:3072 nt
	global_store_dwordx2 v3, v[100:101], s[10:11] nt
	global_store_dwordx2 v3, v[102:103], s[10:11] offset:512 nt
	global_store_dwordx2 v3, v[104:105], s[10:11] offset:1024 nt
	global_store_dwordx2 v3, v[106:107], s[10:11] offset:1536 nt
	s_add_u32 s8, s8, s34
	s_addc_u32 s9, s9, 0
	s_add_u32 s10, s10, s35
	s_addc_u32 s11, s11, 0
	s_add_i32 s4, s4, s5
	s_cmp_ge_i32 s4, s52
	s_cbranch_scc1 .Lmy_lns0_done
; DI unsigned cvtpk(float lo, float hi) { f32x2_t v = {lo, hi}; bf16x2_t b = __builtin_convertvector(v, bf16x2_t); return __builtin_bit_cast(unsigned, b); }
; DI void ln_row2(float* y0, float* y1, bf16_t* xb0, bf16_t* xb1, const float* g, const float* b, int lane) {
;     f32x4* xr0 = (f32x4*)y0 + lane; f32x4* xr1 = (f32x4*)y1 + lane;
;     f32x4 v0[4], v1[4]; float s0 = 0.f, s1 = 0.f;
; #pragma unroll
;     for (int j = 0; j < 4; ++j) { v0[j] = xr0[64 * j]; v1[j] = xr1[64 * j]; }
; #pragma unroll
;     for (int j = 0; j < 4; ++j) { s0 += (v0[j].x + v0[j].y) + (v0[j].z + v0[j].w); s1 += (v1[j].x + v1[j].y) + (v1[j].z + v1[j].w); }
; #pragma unroll
;     for (int o = 1; o < 64; o <<= 1) { s0 += __shfl_xor(s0, o); s1 += __shfl_xor(s1, o); }
;     const float m0 = s0 * (1.f / DM), m1 = s1 * (1.f / DM); float q0 = 0.f, q1 = 0.f;
; #pragma unroll
;     for (int j = 0; j < 4; ++j) { v0[j] = v0[j] - m0; v1[j] = v1[j] - m1;
;         q0 += (v0[j].x * v0[j].x + v0[j].y * v0[j].y) + (v0[j].z * v0[j].z + v0[j].w * v0[j].w);
;         q1 += (v1[j].x * v1[j].x + v1[j].y * v1[j].y) + (v1[j].z * v1[j].z + v1[j].w * v1[j].w); }
; #pragma unroll
;     for (int o = 1; o < 64; o <<= 1) { q0 += __shfl_xor(q0, o); q1 += __shfl_xor(q1, o); }
;     const float r0 = 1.f / sqrtf(q0 * (1.f / DM) + EPS), r1 = 1.f / sqrtf(q1 * (1.f / DM) + EPS);
;     u32x2* o80 = (u32x2*)xb0 + lane; u32x2* o81 = (u32x2*)xb1 + lane;
; #pragma unroll
;     for (int j = 0; j < 4; ++j) {
;         const f32x4 gg = ((const f32x4*)g)[lane + 64 * j], bb = ((const f32x4*)b)[lane + 64 * j];
;         const f32x4 a = v0[j] * r0 * gg + bb, c = v1[j] * r1 * gg + bb;
;         xr0[64 * j] = a; xr1[64 * j] = c;
;         u32x2 w; w.x = cvtpk(a.x, a.y); w.y = cvtpk(a.z, a.w); o80[64 * j] = w;
;         u32x2 w2; w2.x = cvtpk(c.x, c.y); w2.y = cvtpk(c.z, c.w); o81[64 * j] = w2;
;     }
.Lmy_lns0_b1:
	s_cmp_ge_i32 s54, s52
	s_cbranch_scc1 .Lmy_lns0_n1
	global_load_dwordx4 v[36:39], v2, s[6:7] nt
	global_load_dwordx4 v[40:43], v2, s[6:7] offset:1024 nt
	global_load_dwordx4 v[44:47], v2, s[6:7] offset:2048 nt
	global_load_dwordx4 v[48:51], v2, s[6:7] offset:3072 nt
	s_add_u32 s6, s6, s34
	s_addc_u32 s7, s7, 0
	s_add_i32 s54, s54, s5
.Lmy_lns0_n1:
	s_waitcnt vmcnt(16)
	v_add_f32_e32 v84, v52, v53
	v_add_f32_e32 v85, v54, v55
	v_add_f32_e32 v86, v56, v57
	v_add_f32_e32 v87, v58, v59
	v_add_f32_e32 v88, v60, v61
	v_add_f32_e32 v89, v62, v63
	v_add_f32_e32 v90, v64, v65
	v_add_f32_e32 v91, v66, v67
	v_add_f32_e32 v84, v84, v85
	v_add_f32_e32 v86, v86, v87
	v_add_f32_e32 v88, v88, v89
	v_add_f32_e32 v90, v90, v91
	v_add_f32_e32 v84, v84, v86
	v_add_f32_e32 v88, v88, v90
	v_add_f32_e32 v84, v84, v88
	s_nop 1
	v_add_f32_dpp v84, v84, v84 quad_perm:[1,0,3,2] row_mask:0xf bank_mask:0xf
	s_nop 1
	v_add_f32_dpp v84, v84, v84 quad_perm:[2,3,0,1] row_mask:0xf bank_mask:0xf
	s_nop 1
	v_add_f32_dpp v84, v84, v84 row_half_mirror row_mask:0xf bank_mask:0xf
	s_nop 1
	v_add_f32_dpp v84, v84, v84 row_mirror row_mask:0xf bank_mask:0xf
	s_nop 1
	v_add_f32_dpp v84, v84, v84 row_bcast:15 row_mask:0xa bank_mask:0xf
	s_nop 1
	v_add_f32_dpp v84, v84, v84 row_bcast:31 row_mask:0xc bank_mask:0xf
	s_nop 1
	v_readlane_b32 s55, v84, 63
	s_nop 1
	v_mov_b32_e32 v85, s55
	v_mul_f32_e32 v85, 0x3a800000, v85
	v_sub_f32_e32 v52, v52, v85
	v_sub_f32_e32 v53, v53, v85
	v_sub_f32_e32 v54, v54, v85
	v_sub_f32_e32 v55, v55, v85
	v_sub_f32_e32 v56, v56, v85
	v_sub_f32_e32 v57, v57, v85
	v_sub_f32_e32 v58, v58, v85
	v_sub_f32_e32 v59, v59, v85
	v_sub_f32_e32 v60, v60, v85
	v_sub_f32_e32 v61, v61, v85
	v_sub_f32_e32 v62, v62, v85
	v_sub_f32_e32 v63, v63, v85
	v_sub_f32_e32 v64, v64, v85
	v_sub_f32_e32 v65, v65, v85
	v_sub_f32_e32 v66, v66, v85
	v_sub_f32_e32 v67, v67, v85
	v_mul_f32_e32 v88, v52, v52
	v_mul_f32_e32 v89, v53, v53
	v_mul_f32_e32 v90, v54, v54
	v_mul_f32_e32 v91, v55, v55
	v_fmac_f32_e32 v88, v56, v56
	v_fmac_f32_e32 v89, v57, v57
	v_fmac_f32_e32 v90, v58, v58
	v_fmac_f32_e32 v91, v59, v59
	v_fmac_f32_e32 v88, v60, v60
	v_fmac_f32_e32 v89, v61, v61
	v_fmac_f32_e32 v90, v62, v62
	v_fmac_f32_e32 v91, v63, v63
	v_fmac_f32_e32 v88, v64, v64
	v_fmac_f32_e32 v89, v65, v65
	v_fmac_f32_e32 v90, v66, v66
	v_fmac_f32_e32 v91, v67, v67
	v_add_f32_e32 v88, v88, v89
	v_add_f32_e32 v90, v90, v91
	v_add_f32_e32 v88, v88, v90
	s_nop 1
	v_add_f32_dpp v88, v88, v88 quad_perm:[1,0,3,2] row_mask:0xf bank_mask:0xf
	s_nop 1
	v_add_f32_dpp v88, v88, v88 quad_perm:[2,3,0,1] row_mask:0xf bank_mask:0xf
	s_nop 1
	v_add_f32_dpp v88, v88, v88 row_half_mirror row_mask:0xf bank_mask:0xf
	s_nop 1
	v_add_f32_dpp v88, v88, v88 row_mirror row_mask:0xf bank_mask:0xf
	s_nop 1
	v_add_f32_dpp v88, v88, v88 row_bcast:15 row_mask:0xa bank_mask:0xf
	s_nop 1
	v_add_f32_dpp v88, v88, v88 row_bcast:31 row_mask:0xc bank_mask:0xf
	s_nop 1
	v_readlane_b32 s55, v88, 63
	s_nop 1
	v_mov_b32_e32 v89, s55
	v_fmamk_f32 v89, v89, 0x3a800000, v214
	v_rsq_f32_e32 v90, v89
	s_nop 0
	v_mul_f32_e32 v91, v89, v90
	v_mul_f32_e32 v91, v91, v90
	v_mul_f32_e32 v91, -0.5, v91
	v_add_f32_e32 v91, 0x3fc00000, v91
	v_mul_f32_e32 v90, v90, v91
	v_pk_mul_f32 v[52:53], v[52:53], v[90:91] op_sel_hi:[1,0]
	v_pk_mul_f32 v[54:55], v[54:55], v[90:91] op_sel_hi:[1,0]
	v_pk_mul_f32 v[56:57], v[56:57], v[90:91] op_sel_hi:[1,0]
	v_pk_mul_f32 v[58:59], v[58:59], v[90:91] op_sel_hi:[1,0]
	v_pk_mul_f32 v[60:61], v[60:61], v[90:91] op_sel_hi:[1,0]
	v_pk_mul_f32 v[62:63], v[62:63], v[90:91] op_sel_hi:[1,0]
	v_pk_mul_f32 v[64:65], v[64:65], v[90:91] op_sel_hi:[1,0]
	v_pk_mul_f32 v[66:67], v[66:67], v[90:91] op_sel_hi:[1,0]
	v_pk_fma_f32 v[52:53], v[52:53], v[4:5], v[20:21]
	v_pk_fma_f32 v[54:55], v[54:55], v[6:7], v[22:23]
	v_pk_fma_f32 v[56:57], v[56:57], v[8:9], v[24:25]
	v_pk_fma_f32 v[58:59], v[58:59], v[10:11], v[26:27]
	v_pk_fma_f32 v[60:61], v[60:61], v[12:13], v[28:29]
	v_pk_fma_f32 v[62:63], v[62:63], v[14:15], v[30:31]
	v_pk_fma_f32 v[64:65], v[64:65], v[16:17], v[32:33]
	v_pk_fma_f32 v[66:67], v[66:67], v[18:19], v[34:35]
	v_cvt_pk_bf16_f32 v100, v52, v53
	v_cvt_pk_bf16_f32 v101, v54, v55
	v_cvt_pk_bf16_f32 v102, v56, v57
	v_cvt_pk_bf16_f32 v103, v58, v59
	v_cvt_pk_bf16_f32 v104, v60, v61
	v_cvt_pk_bf16_f32 v105, v62, v63
	v_cvt_pk_bf16_f32 v106, v64, v65
	v_cvt_pk_bf16_f32 v107, v66, v67
	global_store_dwordx4 v2, v[52:55], s[8:9] nt
	global_store_dwordx4 v2, v[56:59], s[8:9] offset:1024 nt
	global_store_dwordx4 v2, v[60:63], s[8:9] offset:2048 nt
	global_store_dwordx4 v2, v[64:67], s[8:9] offset:3072 nt
	global_store_dwordx2 v3, v[100:101], s[10:11] nt
	global_store_dwordx2 v3, v[102:103], s[10:11] offset:512 nt
	global_store_dwordx2 v3, v[104:105], s[10:11] offset:1024 nt
	global_store_dwordx2 v3, v[106:107], s[10:11] offset:1536 nt
	s_add_u32 s8, s8, s34
	s_addc_u32 s9, s9, 0
	s_add_u32 s10, s10, s35
	s_addc_u32 s11, s11, 0
	s_add_i32 s4, s4, s5
	s_cmp_ge_i32 s4, s52
	s_cbranch_scc1 .Lmy_lns0_done
; DI unsigned cvtpk(float lo, float hi) { f32x2_t v = {lo, hi}; bf16x2_t b = __builtin_convertvector(v, bf16x2_t); return __builtin_bit_cast(unsigned, b); }
; DI void ln_row2(float* y0, float* y1, bf16_t* xb0, bf16_t* xb1, const float* g, const float* b, int lane) {
;     f32x4* xr0 = (f32x4*)y0 + lane; f32x4* xr1 = (f32x4*)y1 + lane;
;     f32x4 v0[4], v1[4]; float s0 = 0.f, s1 = 0.f;
; #pragma unroll
;     for (int j = 0; j < 4; ++j) { v0[j] = xr0[64 * j]; v1[j] = xr1[64 * j]; }
; #pragma unroll
;     for (int j = 0; j < 4; ++j) { s0 += (v0[j].x + v0[j].y) + (v0[j].z + v0[j].w); s1 += (v1[j].x + v1[j].y) + (v1[j].z + v1[j].w); }
; #pragma unroll
;     for (int o = 1; o < 64; o <<= 1) { s0 += __shfl_xor(s0, o); s1 += __shfl_xor(s1, o); }
;     const float m0 = s0 * (1.f / DM), m1 = s1 * (1.f / DM); float q0 = 0.f, q1 = 0.f;
; #pragma unroll
;     for (int j = 0; j < 4; ++j) { v0[j] = v0[j] - m0; v1[j] = v1[j] - m1;
;         q0 += (v0[j].x * v0[j].x + v0[j].y * v0[j].y) + (v0[j].z * v0[j].z + v0[j].w * v0[j].w);
;         q1 += (v1[j].x * v1[j].x + v1[j].y * v1[j].y) + (v1[j].z * v1[j].z + v1[j].w * v1[j].w); }
; #pragma unroll
;     for (int o = 1; o < 64; o <<= 1) { q0 += __shfl_xor(q0, o); q1 += __shfl_xor(q1, o); }
;     const float r0 = 1.f / sqrtf(q0 * (1.f / DM) + EPS), r1 = 1.f / sqrtf(q1 * (1.f / DM) + EPS);
;     u32x2* o80 = (u32x2*)xb0 + lane; u32x2* o81 = (u32x2*)xb1 + lane;
; #pragma unroll
;     for (int j = 0; j < 4; ++j) {
;         const f32x4 gg = ((const f32x4*)g)[lane + 64 * j], bb = ((const f32x4*)b)[lane + 64 * j];
;         const f32x4 a = v0[j] * r0 * gg + bb, c = v1[j] * r1 * gg + bb;
;         xr0[64 * j] = a; xr1[64 * j] = c;
;         u32x2 w; w.x = cvtpk(a.x, a.y); w.y = cvtpk(a.z, a.w); o80[64 * j] = w;
;         u32x2 w2; w2.x = cvtpk(c.x, c.y); w2.y = cvtpk(c.z, c.w); o81[64 * j] = w2;
;     }
.Lmy_lns0_b2:
	s_cmp_ge_i32 s54, s52
	s_cbranch_scc1 .Lmy_lns0_n2
	global_load_dwordx4 v[52:55], v2, s[6:7] nt
	global_load_dwordx4 v[56:59], v2, s[6:7] offset:1024 nt
	global_load_dwordx4 v[60:63], v2, s[6:7] offset:2048 nt
	global_load_dwordx4 v[64:67], v2, s[6:7] offset:3072 nt
	s_add_u32 s6, s6, s34
	s_addc_u32 s7, s7, 0
	s_add_i32 s54, s54, s5
.Lmy_lns0_n2:
	s_waitcnt vmcnt(16)
	v_add_f32_e32 v84, v68, v69
	v_add_f32_e32 v85, v70, v71
	v_add_f32_e32 v86, v72, v73
	v_add_f32_e32 v87, v74, v75
	v_add_f32_e32 v88, v76, v77
	v_add_f32_e32 v89, v78, v79
	v_add_f32_e32 v90, v80, v81
	v_add_f32_e32 v91, v82, v83
	v_add_f32_e32 v84, v84, v85
	v_add_f32_e32 v86, v86, v87
	v_add_f32_e32 v88, v88, v89
	v_add_f32_e32 v90, v90, v91
	v_add_f32_e32 v84, v84, v86
	v_add_f32_e32 v88, v88, v90
	v_add_f32_e32 v84, v84, v88
	s_nop 1
	v_add_f32_dpp v84, v84, v84 quad_perm:[1,0,3,2] row_mask:0xf bank_mask:0xf
	s_nop 1
	v_add_f32_dpp v84, v84, v84 quad_perm:[2,3,0,1] row_mask:0xf bank_mask:0xf
	s_nop 1
	v_add_f32_dpp v84, v84, v84 row_half_mirror row_mask:0xf bank_mask:0xf
	s_nop 1
	v_add_f32_dpp v84, v84, v84 row_mirror row_mask:0xf bank_mask:0xf
	s_nop 1
	v_add_f32_dpp v84, v84, v84 row_bcast:15 row_mask:0xa bank_mask:0xf
	s_nop 1
	v_add_f32_dpp v84, v84, v84 row_bcast:31 row_mask:0xc bank_mask:0xf
	s_nop 1
	v_readlane_b32 s55, v84, 63
	s_nop 1
	v_mov_b32_e32 v85, s55
	v_mul_f32_e32 v85, 0x3a800000, v85
	v_sub_f32_e32 v68, v68, v85
	v_sub_f32_e32 v69, v69, v85
	v_sub_f32_e32 v70, v70, v85
	v_sub_f32_e32 v71, v71, v85
	v_sub_f32_e32 v72, v72, v85
	v_sub_f32_e32 v73, v73, v85
	v_sub_f32_e32 v74, v74, v85
	v_sub_f32_e32 v75, v75, v85
	v_sub_f32_e32 v76, v76, v85
	v_sub_f32_e32 v77, v77, v85
	v_sub_f32_e32 v78, v78, v85
	v_sub_f32_e32 v79, v79, v85
	v_sub_f32_e32 v80, v80, v85
	v_sub_f32_e32 v81, v81, v85
	v_sub_f32_e32 v82, v82, v85
	v_sub_f32_e32 v83, v83, v85
	v_mul_f32_e32 v88, v68, v68
	v_mul_f32_e32 v89, v69, v69
	v_mul_f32_e32 v90, v70, v70
	v_mul_f32_e32 v91, v71, v71
	v_fmac_f32_e32 v88, v72, v72
	v_fmac_f32_e32 v89, v73, v73
	v_fmac_f32_e32 v90, v74, v74
	v_fmac_f32_e32 v91, v75, v75
	v_fmac_f32_e32 v88, v76, v76
	v_fmac_f32_e32 v89, v77, v77
	v_fmac_f32_e32 v90, v78, v78
	v_fmac_f32_e32 v91, v79, v79
	v_fmac_f32_e32 v88, v80, v80
	v_fmac_f32_e32 v89, v81, v81
	v_fmac_f32_e32 v90, v82, v82
	v_fmac_f32_e32 v91, v83, v83
	v_add_f32_e32 v88, v88, v89
	v_add_f32_e32 v90, v90, v91
	v_add_f32_e32 v88, v88, v90
	s_nop 1
	v_add_f32_dpp v88, v88, v88 quad_perm:[1,0,3,2] row_mask:0xf bank_mask:0xf
	s_nop 1
	v_add_f32_dpp v88, v88, v88 quad_perm:[2,3,0,1] row_mask:0xf bank_mask:0xf
	s_nop 1
	v_add_f32_dpp v88, v88, v88 row_half_mirror row_mask:0xf bank_mask:0xf
	s_nop 1
	v_add_f32_dpp v88, v88, v88 row_mirror row_mask:0xf bank_mask:0xf
	s_nop 1
	v_add_f32_dpp v88, v88, v88 row_bcast:15 row_mask:0xa bank_mask:0xf
	s_nop 1
	v_add_f32_dpp v88, v88, v88 row_bcast:31 row_mask:0xc bank_mask:0xf
	s_nop 1
	v_readlane_b32 s55, v88, 63
	s_nop 1
	v_mov_b32_e32 v89, s55
	v_fmamk_f32 v89, v89, 0x3a800000, v214
	v_rsq_f32_e32 v90, v89
	s_nop 0
	v_mul_f32_e32 v91, v89, v90
	v_mul_f32_e32 v91, v91, v90
	v_mul_f32_e32 v91, -0.5, v91
	v_add_f32_e32 v91, 0x3fc00000, v91
	v_mul_f32_e32 v90, v90, v91
	v_pk_mul_f32 v[68:69], v[68:69], v[90:91] op_sel_hi:[1,0]
	v_pk_mul_f32 v[70:71], v[70:71], v[90:91] op_sel_hi:[1,0]
	v_pk_mul_f32 v[72:73], v[72:73], v[90:91] op_sel_hi:[1,0]
	v_pk_mul_f32 v[74:75], v[74:75], v[90:91] op_sel_hi:[1,0]
	v_pk_mul_f32 v[76:77], v[76:77], v[90:91] op_sel_hi:[1,0]
	v_pk_mul_f32 v[78:79], v[78:79], v[90:91] op_sel_hi:[1,0]
	v_pk_mul_f32 v[80:81], v[80:81], v[90:91] op_sel_hi:[1,0]
	v_pk_mul_f32 v[82:83], v[82:83], v[90:91] op_sel_hi:[1,0]
	v_pk_fma_f32 v[68:69], v[68:69], v[4:5], v[20:21]
	v_pk_fma_f32 v[70:71], v[70:71], v[6:7], v[22:23]
	v_pk_fma_f32 v[72:73], v[72:73], v[8:9], v[24:25]
	v_pk_fma_f32 v[74:75], v[74:75], v[10:11], v[26:27]
	v_pk_fma_f32 v[76:77], v[76:77], v[12:13], v[28:29]
	v_pk_fma_f32 v[78:79], v[78:79], v[14:15], v[30:31]
	v_pk_fma_f32 v[80:81], v[80:81], v[16:17], v[32:33]
	v_pk_fma_f32 v[82:83], v[82:83], v[18:19], v[34:35]
	v_cvt_pk_bf16_f32 v100, v68, v69
	v_cvt_pk_bf16_f32 v101, v70, v71
	v_cvt_pk_bf16_f32 v102, v72, v73
	v_cvt_pk_bf16_f32 v103, v74, v75
	v_cvt_pk_bf16_f32 v104, v76, v77
	v_cvt_pk_bf16_f32 v105, v78, v79
	v_cvt_pk_bf16_f32 v106, v80, v81
	v_cvt_pk_bf16_f32 v107, v82, v83
	global_store_dwordx4 v2, v[68:71], s[8:9] nt
	global_store_dwordx4 v2, v[72:75], s[8:9] offset:1024 nt
	global_store_dwordx4 v2, v[76:79], s[8:9] offset:2048 nt
	global_store_dwordx4 v2, v[80:83], s[8:9] offset:3072 nt
	global_store_dwordx2 v3, v[100:101], s[10:11] nt
	global_store_dwordx2 v3, v[102:103], s[10:11] offset:512 nt
	global_store_dwordx2 v3, v[104:105], s[10:11] offset:1024 nt
	global_store_dwordx2 v3, v[106:107], s[10:11] offset:1536 nt
	s_add_u32 s8, s8, s34
	s_addc_u32 s9, s9, 0
	s_add_u32 s10, s10, s35
	s_addc_u32 s11, s11, 0
	s_add_i32 s4, s4, s5
	s_cmp_ge_i32 s4, s52
	s_cbranch_scc1 .Lmy_lns0_done
	s_branch .Lmy_lns0_b0
.Lmy_lns0_done:
.LBB0_384:
	s_or_b64 exec, exec, s[42:43]

; DI void ln_phase(unsigned char* lds, int l, int which) {
;     ...
;         __syncthreads();
;         for (int m = MP + bid * 64 + wid; m < MP + bid * 64 + 64; m += 16) ln_row2(Y + (size_t)m * DM, Y + (size_t)(m + 8) * DM, XB + (size_t)m * DM, XB + (size_t)(m + 8) * DM, g, b, lane);
.LBB0_2178:
	s_or_b64 exec, exec, s[40:41]
	s_lshl_b32 s4, s38, 6
	v_add_u32_e32 v2, s4, v162
	v_add_u32_e32 v34, 0x8000, v2
	s_add_i32 s4, s4, 0x8040
	v_cmp_gt_i32_e32 vcc, s4, v34
	s_barrier
	s_and_saveexec_b64 s[42:43], vcc
	s_mov_b32 s5, 0xf800000
	s_mov_b32 s8, 0x3a00000
	s_mov_b64 s[10:11], 0x8000
	s_mov_b64 s[50:51], 0x10000
	s_cbranch_execz .LBB0_2181
	s_mov_b64 s[42:43], exec
	s_add_u32 s50, s46, 0x3a00000
	s_addc_u32 s51, s47, 0
	v_readfirstlane_b32 s4, v162
	s_lshl_b32 s6, s38, 6
	s_add_i32 s4, s4, s6
	s_add_i32 s4, s4, 0x8000
	s_add_i32 s52, s6, 0x8040
	s_mov_b32 s5, 8
	v_lshlrev_b32_e32 v2, 4, v1
	v_lshlrev_b32_e32 v3, 3, v1
	global_load_dwordx4 v[4:7], v2, s[56:57]
	global_load_dwordx4 v[8:11], v2, s[56:57] offset:1024
	global_load_dwordx4 v[12:15], v2, s[56:57] offset:2048
	global_load_dwordx4 v[16:19], v2, s[56:57] offset:3072
	global_load_dwordx4 v[20:23], v2, s[48:49]
	global_load_dwordx4 v[24:27], v2, s[48:49] offset:1024
	global_load_dwordx4 v[28:31], v2, s[48:49] offset:2048
	global_load_dwordx4 v[32:35], v2, s[48:49] offset:3072
	s_lshl_b32 s34, s5, 12
	s_lshl_b32 s35, s5, 11
	s_lshl_b32 s6, s4, 12
	s_add_u32 s8, s44, s6
	s_addc_u32 s9, s45, 0
	s_lshl_b32 s6, s4, 11
	s_add_u32 s10, s50, s6
	s_addc_u32 s11, s51, 0
	s_mov_b32 s6, s8
	s_mov_b32 s7, s9
	s_mov_b32 s54, s4
	global_load_dwordx4 v[36:39], v2, s[6:7] nt
	global_load_dwordx4 v[40:43], v2, s[6:7] offset:1024 nt
	global_load_dwordx4 v[44:47], v2, s[6:7] offset:2048 nt
	global_load_dwordx4 v[48:51], v2, s[6:7] offset:3072 nt
	s_add_u32 s6, s6, s34
	s_addc_u32 s7, s7, 0
	s_add_i32 s54, s54, s5
	global_load_dwordx4 v[52:55], v2, s[6:7] nt
	global_load_dwordx4 v[56:59], v2, s[6:7] offset:1024 nt
	global_load_dwordx4 v[60:63], v2, s[6:7] offset:2048 nt
	global_load_dwordx4 v[64:67], v2, s[6:7] offset:3072 nt
	s_add_u32 s6, s6, s34
	s_addc_u32 s7, s7, 0
	s_add_i32 s54, s54, s5
	s_waitcnt vmcnt(4)

; DI void ln_phase(unsigned char* lds, int l, int which) {
;     ...
;         __syncthreads();
;         for (int m = MP + bid * 64 + wid; m < MP + bid * 64 + 64; m += 16) ln_row2(Y + (size_t)m * DM, Y + (size_t)(m + 8) * DM, XB + (size_t)m * DM, XB + (size_t)(m + 8) * DM, g, b, lane);
.LBB0_2449:
	s_or_b64 exec, exec, s[40:41]
	s_lshl_b32 s4, s70, 6
	v_add_u32_e32 v2, s4, v162
	v_add_u32_e32 v34, 0x8000, v2
	s_add_i32 s4, s4, 0x8040
	v_cmp_gt_i32_e32 vcc, s4, v34
	s_barrier
	s_and_saveexec_b64 s[42:43], vcc
	s_mov_b32 s5, 0xf800000
	s_mov_b32 s8, 0x3a00000
	s_mov_b64 s[10:11], 0x8000
	s_mov_b64 s[50:51], 0x10000
	s_cbranch_execz .LBB0_2452
	s_mov_b64 s[42:43], exec
	s_add_u32 s50, s46, 0x3a00000
	s_addc_u32 s51, s47, 0
	v_readfirstlane_b32 s4, v162
	s_lshl_b32 s6, s70, 6
	s_add_i32 s4, s4, s6
	s_add_i32 s4, s4, 0x8000
	s_add_i32 s52, s6, 0x8040
	s_mov_b32 s5, 8
	v_lshlrev_b32_e32 v2, 4, v1
	v_lshlrev_b32_e32 v3, 3, v1
	global_load_dwordx4 v[4:7], v2, s[56:57]
	global_load_dwordx4 v[8:11], v2, s[56:57] offset:1024
	global_load_dwordx4 v[12:15], v2, s[56:57] offset:2048
	global_load_dwordx4 v[16:19], v2, s[56:57] offset:3072
	global_load_dwordx4 v[20:23], v2, s[48:49]
	global_load_dwordx4 v[24:27], v2, s[48:49] offset:1024
	global_load_dwordx4 v[28:31], v2, s[48:49] offset:2048
	global_load_dwordx4 v[32:35], v2, s[48:49] offset:3072
	s_lshl_b32 s34, s5, 12
	s_lshl_b32 s35, s5, 11
	s_lshl_b32 s6, s4, 12
	s_add_u32 s8, s44, s6
	s_addc_u32 s9, s45, 0
	s_lshl_b32 s6, s4, 11
	s_add_u32 s10, s50, s6
	s_addc_u32 s11, s51, 0
	s_mov_b32 s6, s8
	s_mov_b32 s7, s9
	s_mov_b32 s54, s4
	global_load_dwordx4 v[36:39], v2, s[6:7] nt
	global_load_dwordx4 v[40:43], v2, s[6:7] offset:1024 nt
	global_load_dwordx4 v[44:47], v2, s[6:7] offset:2048 nt
	global_load_dwordx4 v[48:51], v2, s[6:7] offset:3072 nt
	s_add_u32 s6, s6, s34
	s_addc_u32 s7, s7, 0
	s_add_i32 s54, s54, s5
	global_load_dwordx4 v[52:55], v2, s[6:7] nt
	global_load_dwordx4 v[56:59], v2, s[6:7] offset:1024 nt
	global_load_dwordx4 v[60:63], v2, s[6:7] offset:2048 nt
	global_load_dwordx4 v[64:67], v2, s[6:7] offset:3072 nt
	s_add_u32 s6, s6, s34
	s_addc_u32 s7, s7, 0
	s_add_i32 s54, s54, s5
	s_waitcnt vmcnt(4)
